# phase-4 q-up nope tiles also stored via wave-private LDS transpose (row-contiguous dwordx4)
# baseline (speedup 1.0000x reference)
.LBB0_1709:
	s_andn2_b64 vcc, exec, s[0:1]
	s_cbranch_vccnz .LBB0_1638
	s_mul_hi_i32 s30, s29, 0x2aaaaaab
	s_lshr_b32 s0, s30, 31
	s_add_i32 s30, s30, s0
	s_mul_i32 s0, s30, -6
	s_add_i32 s12, s29, s0
	s_lshl_b32 s0, s30, 7
	s_ashr_i32 s1, s0, 31
	s_lshl_b64 s[6:7], s[0:1], 9
	s_add_u32 s6, s16, s6
	v_mov_b32_e32 v49, v186
	s_addc_u32 s7, s17, s7
	s_ashr_i32 s13, s12, 31
	s_lshl_b64 s[12:13], s[12:13], 16
	v_lshlrev_b32_e32 v16, 4, v49
	v_ashrrev_i32_e32 v50, 3, v49
	v_and_b32_e32 v48, 0x70, v16
	s_add_u32 s12, s24, s12
	v_lshl_or_b32 v132, v50, 9, v48
	s_addc_u32 s13, s25, s13
	v_add_u32_e32 v133, 0x4000, v132
	v_add_u32_e32 v134, 0x8000, v132
	v_add_u32_e32 v135, 0xc000, v132
	s_waitcnt vmcnt(63) expcnt(7) lgkmcnt(15)
	s_barrier
	global_load_dwordx4 v[16:19], v132, s[6:7]
	global_load_dwordx4 v[20:23], v133, s[6:7]
	global_load_dwordx4 v[24:27], v134, s[6:7]
	global_load_dwordx4 v[28:31], v135, s[6:7]
	global_load_dwordx4 v[32:35], v132, s[12:13]
	global_load_dwordx4 v[36:39], v133, s[12:13]
	global_load_dwordx4 v[40:43], v134, s[12:13]
	global_load_dwordx4 v[44:47], v135, s[12:13]
	v_mad_u64_u32 v[130:131], s[34:35], v50, s43, v[48:49]
	s_waitcnt vmcnt(7)
	ds_write_b128 v130, v[16:19]
	s_waitcnt vmcnt(6)
	ds_write_b128 v130, v[20:23] offset:4608
	s_waitcnt vmcnt(5)
	ds_write_b128 v130, v[24:27] offset:9216
	s_waitcnt vmcnt(4)
	ds_write_b128 v130, v[28:31] offset:13824
	s_waitcnt vmcnt(3)
	ds_write_b128 v130, v[32:35] offset:36864
	s_waitcnt vmcnt(2)
	ds_write_b128 v130, v[36:39] offset:41472
	s_waitcnt vmcnt(1)
	ds_write_b128 v130, v[40:43] offset:46080
	s_waitcnt vmcnt(0)
	ds_write_b128 v130, v[44:47] offset:50688
	global_load_dwordx4 v[96:99], v132, s[6:7] offset:128
	global_load_dwordx4 v[100:103], v133, s[6:7] offset:128
	global_load_dwordx4 v[104:107], v134, s[6:7] offset:128
	global_load_dwordx4 v[108:111], v135, s[6:7] offset:128
	v_lshrrev_b32_e32 v18, 1, v49
	v_and_b32_e32 v17, 0x5f, v49
	v_and_b32_e32 v16, 16, v18
	v_mad_u32_u24 v131, v17, s43, v16
	v_and_b32_e32 v17, 31, v49
	v_and_or_b32 v17, v18, s44, v17
	v_mad_u64_u32 v[128:129], s[34:35], v17, s43, v[16:17]
	global_load_dwordx4 v[64:67], v132, s[12:13] offset:128
	global_load_dwordx4 v[68:71], v133, s[12:13] offset:128
	global_load_dwordx4 v[72:75], v134, s[12:13] offset:128
	global_load_dwordx4 v[76:79], v135, s[12:13] offset:128
	s_waitcnt lgkmcnt(0)
	s_barrier
	ds_read_b128 v[16:19], v128
	ds_read_b128 v[84:87], v131 offset:41472
	ds_read_b128 v[80:83], v128 offset:4608
	ds_read_b128 v[136:139], v128 offset:32
	s_waitcnt lgkmcnt(2)
	v_mfma_f32_32x32x16_bf16 v[48:63], v[16:19], v[84:87], v[0:15]
	ds_read_b128 v[88:91], v131 offset:36864
	ds_read_b128 v[140:143], v128 offset:4640
	ds_read_b128 v[156:159], v131 offset:36896
	ds_read_b128 v[220:223], v131 offset:41504
	v_add_u32_e32 v129, 0xd800, v130
	s_waitcnt lgkmcnt(3)
	v_mfma_f32_32x32x16_bf16 v[32:47], v[16:19], v[88:91], v[0:15]
	v_mfma_f32_32x32x16_bf16 v[16:31], v[80:83], v[88:91], v[0:15]
	v_mfma_f32_32x32x16_bf16 v[0:15], v[80:83], v[84:87], v[0:15]
	s_waitcnt lgkmcnt(1)
	v_mfma_f32_32x32x16_bf16 v[32:47], v[136:139], v[156:159], v[32:47]
	s_waitcnt lgkmcnt(0)
	v_mfma_f32_32x32x16_bf16 v[48:63], v[136:139], v[220:223], v[48:63]
	v_mfma_f32_32x32x16_bf16 v[16:31], v[140:143], v[156:159], v[16:31]
	v_mfma_f32_32x32x16_bf16 v[0:15], v[140:143], v[220:223], v[0:15]
	ds_read_b128 v[224:227], v128 offset:64
	ds_read_b128 v[228:231], v128 offset:4672
	ds_read_b128 v[232:235], v131 offset:36928
	ds_read_b128 v[236:239], v131 offset:41536
	s_waitcnt lgkmcnt(1)
	v_mfma_f32_32x32x16_bf16 v[32:47], v[224:227], v[232:235], v[32:47]
	s_waitcnt lgkmcnt(0)
	v_mfma_f32_32x32x16_bf16 v[48:63], v[224:227], v[236:239], v[48:63]
	v_mfma_f32_32x32x16_bf16 v[16:31], v[228:231], v[232:235], v[16:31]
	v_mfma_f32_32x32x16_bf16 v[0:15], v[228:231], v[236:239], v[0:15]
	global_load_dwordx4 v[112:115], v132, s[6:7] offset:256
	global_load_dwordx4 v[116:119], v133, s[6:7] offset:256
	global_load_dwordx4 v[120:123], v134, s[6:7] offset:256
	global_load_dwordx4 v[124:127], v135, s[6:7] offset:256
	global_load_dwordx4 v[80:83], v132, s[12:13] offset:256
	global_load_dwordx4 v[84:87], v133, s[12:13] offset:256
	global_load_dwordx4 v[88:91], v134, s[12:13] offset:256
	global_load_dwordx4 v[92:95], v135, s[12:13] offset:256
	s_waitcnt vmcnt(15)
	ds_write_b128 v130, v[96:99] offset:18432
	s_waitcnt vmcnt(14)
	ds_write_b128 v130, v[100:103] offset:23040
	s_waitcnt vmcnt(13)
	ds_write_b128 v130, v[104:107] offset:27648
	s_waitcnt vmcnt(12)
	ds_write_b128 v130, v[108:111] offset:32256
	ds_read_b128 v[96:99], v128 offset:96
	ds_read_b128 v[100:103], v128 offset:4704
	ds_read_b128 v[104:107], v131 offset:36960
	ds_read_b128 v[108:111], v131 offset:41568
	s_waitcnt vmcnt(11)
	ds_write_b128 v130, v[64:67] offset:55296
	s_waitcnt vmcnt(10)
	ds_write_b128 v130, v[68:71] offset:59904
	s_waitcnt vmcnt(9)
	ds_write_b128 v130, v[72:75] offset:64512
	s_waitcnt vmcnt(8)
	ds_write_b128 v129, v[76:79] offset:13824
	s_waitcnt lgkmcnt(5)
	v_mfma_f32_32x32x16_bf16 v[32:47], v[96:99], v[104:107], v[32:47]
	s_waitcnt lgkmcnt(0)
	s_barrier
	v_mfma_f32_32x32x16_bf16 v[48:63], v[96:99], v[108:111], v[48:63]
	v_mfma_f32_32x32x16_bf16 v[16:31], v[100:103], v[104:107], v[16:31]
	v_mfma_f32_32x32x16_bf16 v[0:15], v[100:103], v[108:111], v[0:15]
	ds_read_b128 v[64:67], v128 offset:23040
	ds_read_b128 v[72:75], v128 offset:18432
	ds_read_b128 v[68:71], v131 offset:59904
	ds_read_b128 v[76:79], v131 offset:55296
	ds_read_b128 v[96:99], v128 offset:18464
	ds_read_b128 v[100:103], v128 offset:23072
	ds_read_b128 v[104:107], v131 offset:55328
	ds_read_b128 v[108:111], v131 offset:59936
	s_waitcnt lgkmcnt(4)
	v_mfma_f32_32x32x16_bf16 v[32:47], v[72:75], v[76:79], v[32:47]
	v_mfma_f32_32x32x16_bf16 v[48:63], v[72:75], v[68:71], v[48:63]
	v_mfma_f32_32x32x16_bf16 v[16:31], v[64:67], v[76:79], v[16:31]
	v_mfma_f32_32x32x16_bf16 v[0:15], v[64:67], v[68:71], v[0:15]
	global_load_dwordx4 v[136:139], v132, s[6:7] offset:384
	global_load_dwordx4 v[140:143], v133, s[6:7] offset:384
	global_load_dwordx4 v[156:159], v134, s[6:7] offset:384
	global_load_dwordx4 v[220:223], v135, s[6:7] offset:384
	global_load_dwordx4 v[64:67], v132, s[12:13] offset:384
	global_load_dwordx4 v[68:71], v133, s[12:13] offset:384
	global_load_dwordx4 v[72:75], v134, s[12:13] offset:384
	global_load_dwordx4 v[76:79], v135, s[12:13] offset:384
	ds_read_b128 v[224:227], v128 offset:23104
	ds_read_b128 v[132:135], v128 offset:18496
	ds_read_b128 v[228:231], v131 offset:55360
	ds_read_b128 v[232:235], v131 offset:59968
	s_waitcnt vmcnt(15)
	ds_write_b128 v130, v[112:115]
	s_waitcnt vmcnt(14)
	ds_write_b128 v130, v[116:119] offset:4608
	s_waitcnt vmcnt(13)
	ds_write_b128 v130, v[120:123] offset:9216
	s_waitcnt vmcnt(12)
	ds_write_b128 v130, v[124:127] offset:13824
	s_waitcnt lgkmcnt(9)
	v_mfma_f32_32x32x16_bf16 v[16:31], v[100:103], v[104:107], v[16:31]
	s_waitcnt lgkmcnt(8)
	v_mfma_f32_32x32x16_bf16 v[0:15], v[100:103], v[108:111], v[0:15]
	v_mfma_f32_32x32x16_bf16 v[32:47], v[96:99], v[104:107], v[32:47]
	v_mfma_f32_32x32x16_bf16 v[48:63], v[96:99], v[108:111], v[48:63]
	ds_read_b128 v[100:103], v128 offset:23136
	ds_read_b128 v[96:99], v128 offset:18528
	ds_read_b128 v[104:107], v131 offset:55392
	ds_read_b128 v[108:111], v131 offset:60000
	s_waitcnt vmcnt(11)
	ds_write_b128 v130, v[80:83] offset:36864
	s_waitcnt vmcnt(10)
	ds_write_b128 v130, v[84:87] offset:41472
	s_waitcnt vmcnt(9)
	ds_write_b128 v130, v[88:91] offset:46080
	s_waitcnt vmcnt(8)
	ds_write_b128 v130, v[92:95] offset:50688
	s_waitcnt lgkmcnt(13)
	v_mfma_f32_32x32x16_bf16 v[16:31], v[224:227], v[228:231], v[16:31]
	s_waitcnt lgkmcnt(0)
	s_barrier
	v_mfma_f32_32x32x16_bf16 v[0:15], v[224:227], v[232:235], v[0:15]
	v_mfma_f32_32x32x16_bf16 v[16:31], v[100:103], v[104:107], v[16:31]
	v_mfma_f32_32x32x16_bf16 v[0:15], v[100:103], v[108:111], v[0:15]
	ds_read_b128 v[100:103], v128 offset:32
	v_mfma_f32_32x32x16_bf16 v[32:47], v[132:135], v[228:231], v[32:47]
	v_mfma_f32_32x32x16_bf16 v[48:63], v[132:135], v[232:235], v[48:63]
	v_mfma_f32_32x32x16_bf16 v[32:47], v[96:99], v[104:107], v[32:47]
	ds_read_b128 v[104:107], v131 offset:36928
	v_mfma_f32_32x32x16_bf16 v[48:63], v[96:99], v[108:111], v[48:63]
	ds_read_b128 v[96:99], v128
	ds_read_b128 v[80:83], v128 offset:4608
	ds_read_b128 v[84:87], v131 offset:41472
	ds_read_b128 v[108:111], v131 offset:41536
	s_waitcnt lgkmcnt(1)
	v_mfma_f32_32x32x16_bf16 v[48:63], v[96:99], v[84:87], v[48:63]
	v_mfma_f32_32x32x16_bf16 v[0:15], v[80:83], v[84:87], v[0:15]
	ds_read_b128 v[84:87], v128 offset:4640
	ds_read_b128 v[88:91], v131 offset:36864
	s_waitcnt lgkmcnt(0)
	v_mfma_f32_32x32x16_bf16 v[16:31], v[80:83], v[88:91], v[16:31]
	ds_read_b128 v[80:83], v131 offset:41504
	ds_read_b128 v[92:95], v131 offset:36896
	s_waitcnt lgkmcnt(1)
	v_mfma_f32_32x32x16_bf16 v[48:63], v[100:103], v[80:83], v[48:63]
	s_waitcnt lgkmcnt(0)
	v_mfma_f32_32x32x16_bf16 v[16:31], v[84:87], v[92:95], v[16:31]
	v_mfma_f32_32x32x16_bf16 v[0:15], v[84:87], v[80:83], v[0:15]
	v_mfma_f32_32x32x16_bf16 v[32:47], v[96:99], v[88:91], v[32:47]
	ds_read_b128 v[88:91], v128 offset:64
	ds_read_b128 v[96:99], v128 offset:4672
	s_waitcnt vmcnt(7)
	ds_write_b128 v130, v[136:139] offset:18432
	s_waitcnt vmcnt(6)
	ds_write_b128 v130, v[140:143] offset:23040
	s_waitcnt vmcnt(5)
	ds_write_b128 v130, v[156:159] offset:27648
	s_waitcnt vmcnt(4)
	ds_write_b128 v130, v[220:223] offset:32256
	ds_read_b128 v[80:83], v128 offset:96
	v_mfma_f32_32x32x16_bf16 v[32:47], v[100:103], v[92:95], v[32:47]
	ds_read_b128 v[84:87], v128 offset:4704
	ds_read_b128 v[92:95], v131 offset:36960
	ds_read_b128 v[100:103], v131 offset:41568
	s_waitcnt vmcnt(3)
	ds_write_b128 v130, v[64:67] offset:55296
	s_waitcnt vmcnt(2)
	ds_write_b128 v130, v[68:71] offset:59904
	s_waitcnt vmcnt(1)
	ds_write_b128 v130, v[72:75] offset:64512
	s_waitcnt vmcnt(0)
	ds_write_b128 v129, v[76:79] offset:13824
	s_waitcnt lgkmcnt(13)
	v_mfma_f32_32x32x16_bf16 v[32:47], v[88:91], v[104:107], v[32:47]
	s_waitcnt lgkmcnt(0)
	s_barrier
	ds_read_b128 v[64:67], v128 offset:23040
	ds_read_b128 v[72:75], v128 offset:18432
	ds_read_b128 v[68:71], v131 offset:59904
	ds_read_b128 v[76:79], v128 offset:18464
	v_mfma_f32_32x32x16_bf16 v[48:63], v[88:91], v[108:111], v[48:63]
	ds_read_b128 v[88:91], v131 offset:55328
	v_mfma_f32_32x32x16_bf16 v[16:31], v[96:99], v[104:107], v[16:31]
	ds_read_b128 v[104:107], v131 offset:55392
	v_mfma_f32_32x32x16_bf16 v[0:15], v[96:99], v[108:111], v[0:15]
	ds_read_b128 v[96:99], v128 offset:18528
	ds_read_b128 v[108:111], v131 offset:60000
	v_mfma_f32_32x32x16_bf16 v[32:47], v[80:83], v[92:95], v[32:47]
	v_mfma_f32_32x32x16_bf16 v[48:63], v[80:83], v[100:103], v[48:63]
	ds_read_b128 v[80:83], v128 offset:23072
	v_mfma_f32_32x32x16_bf16 v[16:31], v[84:87], v[92:95], v[16:31]
	ds_read_b128 v[92:95], v131 offset:59936
	v_mfma_f32_32x32x16_bf16 v[0:15], v[84:87], v[100:103], v[0:15]
	ds_read_b128 v[84:87], v131 offset:55296
	ds_read_b128 v[100:103], v128 offset:23136
	s_waitcnt lgkmcnt(1)
	v_mfma_f32_32x32x16_bf16 v[32:47], v[72:75], v[84:87], v[32:47]
	v_mfma_f32_32x32x16_bf16 v[48:63], v[72:75], v[68:71], v[48:63]
	ds_read_b128 v[72:75], v131 offset:55360
	v_mfma_f32_32x32x16_bf16 v[16:31], v[64:67], v[84:87], v[16:31]
	ds_read_b128 v[84:87], v131 offset:59968
	v_mfma_f32_32x32x16_bf16 v[0:15], v[64:67], v[68:71], v[0:15]
	ds_read_b128 v[64:67], v128 offset:18496
	ds_read_b128 v[68:71], v128 offset:23104
	s_waitcnt lgkmcnt(0)
	s_barrier
	v_mfma_f32_32x32x16_bf16 v[32:47], v[76:79], v[88:91], v[32:47]
	v_mfma_f32_32x32x16_bf16 v[48:63], v[76:79], v[92:95], v[48:63]
	v_mfma_f32_32x32x16_bf16 v[16:31], v[80:83], v[88:91], v[16:31]
	v_mfma_f32_32x32x16_bf16 v[0:15], v[80:83], v[92:95], v[0:15]
	v_mfma_f32_32x32x16_bf16 v[32:47], v[64:67], v[72:75], v[32:47]
	v_mfma_f32_32x32x16_bf16 v[48:63], v[64:67], v[84:87], v[48:63]
	v_mad_u64_u32 v[64:65], s[6:7], s30, -12, v[154:155]
	s_mulk_i32 s30, 0xffe8
	v_cmp_lt_i32_e32 vcc, 7, v64
	v_add_u32_e32 v160, s30, v218
	v_mfma_f32_32x32x16_bf16 v[16:31], v[68:71], v[72:75], v[16:31]
	v_mfma_f32_32x32x16_bf16 v[0:15], v[68:71], v[84:87], v[0:15]
	v_add_u32_e32 v68, s0, v163
	v_or_b32_e32 v66, v68, v164
	v_ashrrev_i32_e32 v67, 31, v66
	v_mfma_f32_32x32x16_bf16 v[32:47], v[96:99], v[104:107], v[32:47]
	v_mfma_f32_32x32x16_bf16 v[48:63], v[96:99], v[108:111], v[48:63]
	v_mfma_f32_32x32x16_bf16 v[16:31], v[100:103], v[104:107], v[16:31]
	v_mfma_f32_32x32x16_bf16 v[0:15], v[100:103], v[108:111], v[0:15]
	s_nop 7
	s_nop 7
	v_mul_f32_e32 v32, 0x3e16c740, v32
	v_mul_f32_e32 v33, 0x3e16c740, v33
	v_mul_f32_e32 v34, 0x3e16c740, v34
	v_mul_f32_e32 v35, 0x3e16c740, v35
	v_mul_f32_e32 v36, 0x3e16c740, v36
	v_mul_f32_e32 v37, 0x3e16c740, v37
	v_mul_f32_e32 v38, 0x3e16c740, v38
	v_mul_f32_e32 v39, 0x3e16c740, v39
	v_mul_f32_e32 v40, 0x3e16c740, v40
	v_mul_f32_e32 v41, 0x3e16c740, v41
	v_mul_f32_e32 v42, 0x3e16c740, v42
	v_mul_f32_e32 v43, 0x3e16c740, v43
	v_mul_f32_e32 v44, 0x3e16c740, v44
	v_mul_f32_e32 v45, 0x3e16c740, v45
	v_mul_f32_e32 v46, 0x3e16c740, v46
	v_mul_f32_e32 v47, 0x3e16c740, v47
	v_mul_f32_e32 v48, 0x3e16c740, v48
	v_mul_f32_e32 v49, 0x3e16c740, v49
	v_mul_f32_e32 v50, 0x3e16c740, v50
	v_mul_f32_e32 v51, 0x3e16c740, v51
	v_mul_f32_e32 v52, 0x3e16c740, v52
	v_mul_f32_e32 v53, 0x3e16c740, v53
	v_mul_f32_e32 v54, 0x3e16c740, v54
	v_mul_f32_e32 v55, 0x3e16c740, v55
	v_mul_f32_e32 v56, 0x3e16c740, v56
	v_mul_f32_e32 v57, 0x3e16c740, v57
	v_mul_f32_e32 v58, 0x3e16c740, v58
	v_mul_f32_e32 v59, 0x3e16c740, v59
	v_mul_f32_e32 v60, 0x3e16c740, v60
	v_mul_f32_e32 v61, 0x3e16c740, v61
	v_mul_f32_e32 v62, 0x3e16c740, v62
	v_mul_f32_e32 v63, 0x3e16c740, v63
	v_mul_f32_e32 v16, 0x3e16c740, v16
	v_mul_f32_e32 v17, 0x3e16c740, v17
	v_mul_f32_e32 v18, 0x3e16c740, v18
	v_mul_f32_e32 v19, 0x3e16c740, v19
	v_mul_f32_e32 v20, 0x3e16c740, v20
	v_mul_f32_e32 v21, 0x3e16c740, v21
	v_mul_f32_e32 v22, 0x3e16c740, v22
	v_mul_f32_e32 v23, 0x3e16c740, v23
	v_mul_f32_e32 v24, 0x3e16c740, v24
	v_mul_f32_e32 v25, 0x3e16c740, v25
	v_mul_f32_e32 v26, 0x3e16c740, v26
	v_mul_f32_e32 v27, 0x3e16c740, v27
	v_mul_f32_e32 v28, 0x3e16c740, v28
	v_mul_f32_e32 v29, 0x3e16c740, v29
	v_mul_f32_e32 v30, 0x3e16c740, v30
	v_mul_f32_e32 v31, 0x3e16c740, v31
	v_mul_f32_e32 v0, 0x3e16c740, v0
	v_mul_f32_e32 v1, 0x3e16c740, v1
	v_mul_f32_e32 v2, 0x3e16c740, v2
	v_mul_f32_e32 v3, 0x3e16c740, v3
	v_mul_f32_e32 v4, 0x3e16c740, v4
	v_mul_f32_e32 v5, 0x3e16c740, v5
	v_mul_f32_e32 v6, 0x3e16c740, v6
	v_mul_f32_e32 v7, 0x3e16c740, v7
	v_mul_f32_e32 v8, 0x3e16c740, v8
	v_mul_f32_e32 v9, 0x3e16c740, v9
	v_mul_f32_e32 v10, 0x3e16c740, v10
	v_mul_f32_e32 v11, 0x3e16c740, v11
	v_mul_f32_e32 v12, 0x3e16c740, v12
	v_mul_f32_e32 v13, 0x3e16c740, v13
	v_mul_f32_e32 v14, 0x3e16c740, v14
	v_mul_f32_e32 v15, 0x3e16c740, v15
	v_readfirstlane_b32 s30, v64
	s_nop 0
	s_cmp_gt_i32 s30, 7
	s_cbranch_scc1 .Lp4q_orig
	s_nop 15
	v_ashrrev_i32_e32 v65, 31, v64
	v_lshl_add_u64 v[66:67], v[66:67], 3, v[64:65]
	v_mad_u64_u32 v[70:71], s[32:33], v66, s38, v[152:153]
	v_mad_i32_i24 v71, v67, s38, v71
	s_nop 0
	v_readfirstlane_b32 s32, v70
	v_readfirstlane_b32 s33, v71
	v_readfirstlane_b32 s30, v186
	s_lshr_b32 s30, s30, 6
	s_mul_i32 s30, s30, 0x2400
	v_and_b32_e32 v90, 31, v186
	v_bfe_u32 v91, v186, 5, 1
	v_mul_u32_u24_e32 v91, 576, v91
	v_lshl_add_u32 v90, v90, 1, v91
	v_add_u32_e32 v90, s30, v90
	v_and_b32_e32 v92, 63, v186
	v_lshrrev_b32_e32 v93, 3, v92
	v_and_b32_e32 v92, 7, v92
	v_mul_u32_u24_e32 v94, 144, v93
	v_lshl_add_u32 v94, v92, 4, v94
	v_add_u32_e32 v94, s30, v94
	v_mul_u32_u24_e32 v95, 1536, v93
	v_lshl_add_u32 v95, v92, 4, v95
	v_cvt_pk_bf16_f32 v96, v32, v33
	ds_write_b16 v90, v96
	ds_write_b16_d16_hi v90, v96 offset:144
	v_cvt_pk_bf16_f32 v97, v34, v35
	ds_write_b16 v90, v97 offset:288
	ds_write_b16_d16_hi v90, v97 offset:432
	v_cvt_pk_bf16_f32 v98, v36, v37
	ds_write_b16 v90, v98 offset:1152
	ds_write_b16_d16_hi v90, v98 offset:1296
	v_cvt_pk_bf16_f32 v99, v38, v39
	ds_write_b16 v90, v99 offset:1440
	ds_write_b16_d16_hi v90, v99 offset:1584
	v_cvt_pk_bf16_f32 v100, v40, v41
	ds_write_b16 v90, v100 offset:2304
	ds_write_b16_d16_hi v90, v100 offset:2448
	v_cvt_pk_bf16_f32 v101, v42, v43
	ds_write_b16 v90, v101 offset:2592
	ds_write_b16_d16_hi v90, v101 offset:2736
	v_cvt_pk_bf16_f32 v102, v44, v45
	ds_write_b16 v90, v102 offset:3456
	ds_write_b16_d16_hi v90, v102 offset:3600
	v_cvt_pk_bf16_f32 v103, v46, v47
	ds_write_b16 v90, v103 offset:3744
	ds_write_b16_d16_hi v90, v103 offset:3888
	v_cvt_pk_bf16_f32 v104, v48, v49
	ds_write_b16 v90, v104 offset:64
	ds_write_b16_d16_hi v90, v104 offset:208
	v_cvt_pk_bf16_f32 v105, v50, v51
	ds_write_b16 v90, v105 offset:352
	ds_write_b16_d16_hi v90, v105 offset:496
	v_cvt_pk_bf16_f32 v106, v52, v53
	ds_write_b16 v90, v106 offset:1216
	ds_write_b16_d16_hi v90, v106 offset:1360
	v_cvt_pk_bf16_f32 v107, v54, v55
	ds_write_b16 v90, v107 offset:1504
	ds_write_b16_d16_hi v90, v107 offset:1648
	v_cvt_pk_bf16_f32 v108, v56, v57
	ds_write_b16 v90, v108 offset:2368
	ds_write_b16_d16_hi v90, v108 offset:2512
	v_cvt_pk_bf16_f32 v109, v58, v59
	ds_write_b16 v90, v109 offset:2656
	ds_write_b16_d16_hi v90, v109 offset:2800
	v_cvt_pk_bf16_f32 v110, v60, v61
	ds_write_b16 v90, v110 offset:3520
	ds_write_b16_d16_hi v90, v110 offset:3664
	v_cvt_pk_bf16_f32 v111, v62, v63
	ds_write_b16 v90, v111 offset:3808
	ds_write_b16_d16_hi v90, v111 offset:3952
	v_cvt_pk_bf16_f32 v112, v16, v17
	ds_write_b16 v90, v112 offset:4608
	ds_write_b16_d16_hi v90, v112 offset:4752
	v_cvt_pk_bf16_f32 v113, v18, v19
	ds_write_b16 v90, v113 offset:4896
	ds_write_b16_d16_hi v90, v113 offset:5040
	v_cvt_pk_bf16_f32 v114, v20, v21
	ds_write_b16 v90, v114 offset:5760
	ds_write_b16_d16_hi v90, v114 offset:5904
	v_cvt_pk_bf16_f32 v115, v22, v23
	ds_write_b16 v90, v115 offset:6048
	ds_write_b16_d16_hi v90, v115 offset:6192
	v_cvt_pk_bf16_f32 v116, v24, v25
	ds_write_b16 v90, v116 offset:6912
	ds_write_b16_d16_hi v90, v116 offset:7056
	v_cvt_pk_bf16_f32 v117, v26, v27
	ds_write_b16 v90, v117 offset:7200
	ds_write_b16_d16_hi v90, v117 offset:7344
	v_cvt_pk_bf16_f32 v118, v28, v29
	ds_write_b16 v90, v118 offset:8064
	ds_write_b16_d16_hi v90, v118 offset:8208
	v_cvt_pk_bf16_f32 v119, v30, v31
	ds_write_b16 v90, v119 offset:8352
	ds_write_b16_d16_hi v90, v119 offset:8496
	v_cvt_pk_bf16_f32 v120, v0, v1
	ds_write_b16 v90, v120 offset:4672
	ds_write_b16_d16_hi v90, v120 offset:4816
	v_cvt_pk_bf16_f32 v121, v2, v3
	ds_write_b16 v90, v121 offset:4960
	ds_write_b16_d16_hi v90, v121 offset:5104
	v_cvt_pk_bf16_f32 v122, v4, v5
	ds_write_b16 v90, v122 offset:5824
	ds_write_b16_d16_hi v90, v122 offset:5968
	v_cvt_pk_bf16_f32 v123, v6, v7
	ds_write_b16 v90, v123 offset:6112
	ds_write_b16_d16_hi v90, v123 offset:6256
	v_cvt_pk_bf16_f32 v124, v8, v9
	ds_write_b16 v90, v124 offset:6976
	ds_write_b16_d16_hi v90, v124 offset:7120
	v_cvt_pk_bf16_f32 v125, v10, v11
	ds_write_b16 v90, v125 offset:7264
	ds_write_b16_d16_hi v90, v125 offset:7408
	v_cvt_pk_bf16_f32 v126, v12, v13
	ds_write_b16 v90, v126 offset:8128
	ds_write_b16_d16_hi v90, v126 offset:8272
	v_cvt_pk_bf16_f32 v127, v14, v15
	ds_write_b16 v90, v127 offset:8416
	ds_write_b16_d16_hi v90, v127 offset:8560
	s_waitcnt lgkmcnt(0)
	ds_read_b128 v[96:99], v94
	ds_read_b128 v[100:103], v94 offset:1152
	ds_read_b128 v[104:107], v94 offset:2304
	ds_read_b128 v[108:111], v94 offset:3456
	ds_read_b128 v[112:115], v94 offset:4608
	ds_read_b128 v[116:119], v94 offset:5760
	ds_read_b128 v[120:123], v94 offset:6912
	ds_read_b128 v[124:127], v94 offset:8064
	s_waitcnt lgkmcnt(7)
	global_store_dwordx4 v95, v[96:99], s[32:33]
	s_add_u32 s32, s32, 12288
	s_addc_u32 s33, s33, 0
	s_waitcnt lgkmcnt(6)
	global_store_dwordx4 v95, v[100:103], s[32:33]
	s_add_u32 s32, s32, 12288
	s_addc_u32 s33, s33, 0
	s_waitcnt lgkmcnt(5)
	global_store_dwordx4 v95, v[104:107], s[32:33]
	s_add_u32 s32, s32, 12288
	s_addc_u32 s33, s33, 0
	s_waitcnt lgkmcnt(4)
	global_store_dwordx4 v95, v[108:111], s[32:33]
	s_add_u32 s32, s32, 12288
	s_addc_u32 s33, s33, 0
	s_waitcnt lgkmcnt(3)
	global_store_dwordx4 v95, v[112:115], s[32:33]
	s_add_u32 s32, s32, 12288
	s_addc_u32 s33, s33, 0
	s_waitcnt lgkmcnt(2)
	global_store_dwordx4 v95, v[116:119], s[32:33]
	s_add_u32 s32, s32, 12288
	s_addc_u32 s33, s33, 0
	s_waitcnt lgkmcnt(1)
	global_store_dwordx4 v95, v[120:123], s[32:33]
	s_add_u32 s32, s32, 12288
	s_addc_u32 s33, s33, 0
	s_waitcnt lgkmcnt(0)
	global_store_dwordx4 v95, v[124:127], s[32:33]
	s_movk_i32 s34, 0x3fff
	s_branch .LBB0_1638
.Lp4q_orig:
	s_and_saveexec_b64 s[0:1], vcc
	s_xor_b64 s[6:7], exec, s[0:1]
	s_cbranch_execz .LBB0_1712
	v_lshl_or_b32 v70, v66, 4, v165
	v_ashrrev_i32_e32 v71, 31, v70
	v_lshlrev_b64 v[70:71], 2, v[70:71]
	v_lshl_add_u64 v[72:73], s[14:15], 0, v[70:71]
	global_load_dword v65, v[72:73], off
	v_lshl_add_u64 v[70:71], s[10:11], 0, v[70:71]
	global_load_dword v69, v[70:71], off
	v_and_b32_e32 v71, 64, v194
	v_xor_b32_e32 v70, 16, v194
	v_add_u32_e32 v71, 64, v71
	v_cmp_lt_i32_e64 s[0:1], v70, v71
	v_lshl_add_u64 v[66:67], v[66:67], 3, v[160:161]
	s_nop 0
	v_cndmask_b32_e64 v70, v194, v70, s[0:1]
	v_lshlrev_b32_e32 v70, 2, v70
	ds_bpermute_b32 v72, v70, v32
	ds_bpermute_b32 v73, v70, v48
	v_mad_u64_u32 v[70:71], s[0:1], v66, s38, v[152:153]
	v_mad_i32_i24 v71, v67, s38, v71
	s_waitcnt vmcnt(1) lgkmcnt(1)
	v_mul_f32_e32 v66, v65, v72
	s_waitcnt lgkmcnt(0)
	v_mul_f32_e32 v65, v65, v73
	v_cndmask_b32_e64 v66, v66, -v66, s[4:5]
	v_cndmask_b32_e64 v65, v65, -v65, s[4:5]
	s_waitcnt vmcnt(0)
	v_fmac_f32_e32 v66, v69, v32
	v_fmac_f32_e32 v65, v69, v48
	v_cvt_pk_bf16_f32 v66, v66, s0
	v_cvt_pk_bf16_f32 v65, v65, s0
	global_store_short v[70:71], v66, off offset:128
	global_store_short v[70:71], v65, off offset:320
